# GEMM phases: one static s_setprio 1 for waves 0-3 instead of waves 4-7
# speedup vs baseline: 1.0158x; 1.0158x over previous
; #define LAS __attribute__((address_space(3)))
; template <class Epi, bool ALIGN_EPI>
; __device__ __forceinline__ void gemm_phase(LAS unsigned char* lds, const int tid, const Gemm g, const StaticOrder& S, const Epi& E) {
;     const int wid = __builtin_amdgcn_readfirstlane(tid >> 6), lane = tid & 63, wr = wid >> 2, wc = wid & 3, fr = lane & 15, fq = lane >> 4;
.LBB0_76:
	v_readfirstlane_b32 s14, v208
	s_nop 3
	s_bitcmp1_b32 s14, 8
	s_cbranch_scc1 .Lgprio_1
	s_setprio 1

; #define LAS __attribute__((address_space(3)))
; template <class Epi, bool ALIGN_EPI>
; __device__ __forceinline__ void gemm_phase(LAS unsigned char* lds, const int tid, const Gemm g, const StaticOrder& S, const Epi& E) {
;     const int wid = __builtin_amdgcn_readfirstlane(tid >> 6), lane = tid & 63, wr = wid >> 2, wc = wid & 3, fr = lane & 15, fq = lane >> 4;
.LBB0_133:
	s_andn2_b64 vcc, exec, s[0:1]
	s_cbranch_vccnz .LBB0_150
	v_readfirstlane_b32 s12, v208
	s_nop 3
	s_bitcmp1_b32 s12, 8
	s_cbranch_scc1 .Lgprio_2
	s_setprio 1

; #define LAS __attribute__((address_space(3)))
; template <class Epi, bool ALIGN_EPI>
; __device__ __forceinline__ void gemm_phase(LAS unsigned char* lds, const int tid, const Gemm g, const StaticOrder& S, const Epi& E) {
;     const int wid = __builtin_amdgcn_readfirstlane(tid >> 6), lane = tid & 63, wr = wid >> 2, wc = wid & 3, fr = lane & 15, fq = lane >> 4;
.LBB0_170:
	v_readfirstlane_b32 s20, v208
	s_nop 3
	s_bitcmp1_b32 s20, 8
	s_cbranch_scc1 .Lgprio_3
	s_setprio 1

; #define LAS __attribute__((address_space(3)))
; template <class Epi, bool ALIGN_EPI>
; __device__ __forceinline__ void gemm_phase(LAS unsigned char* lds, const int tid, const Gemm g, const StaticOrder& S, const Epi& E) {
;     const int wid = __builtin_amdgcn_readfirstlane(tid >> 6), lane = tid & 63, wr = wid >> 2, wc = wid & 3, fr = lane & 15, fq = lane >> 4;
.LBB0_231:
	v_readfirstlane_b32 s7, v208
	s_nop 3
	s_bitcmp1_b32 s7, 8
	s_cbranch_scc1 .Lgprio_4
	s_setprio 1

; #define LAS __attribute__((address_space(3)))
; template <class Epi, bool ALIGN_EPI>
; __device__ __forceinline__ void gemm_phase(LAS unsigned char* lds, const int tid, const Gemm g, const StaticOrder& S, const Epi& E) {
;     const int wid = __builtin_amdgcn_readfirstlane(tid >> 6), lane = tid & 63, wr = wid >> 2, wc = wid & 3, fr = lane & 15, fq = lane >> 4;
.LBB0_649:
	v_readlane_b32 s0, v248, 3
	s_cmp_gt_i32 s0, 0
	s_mov_b64 s[0:1], -1
	s_cbranch_scc0 .LBB0_680
	v_readlane_b32 s0, v249, 24
	v_readfirstlane_b32 s8, v208
	s_nop 3
	s_bitcmp1_b32 s8, 8
	s_cbranch_scc1 .Lgprio_5
	s_setprio 1
